# EpiConv v3: second half's PS rows prefetched during the first half's last block, store predicates computed without exec save/restore
# baseline (speedup 1.0000x reference)
;     __device__ __forceinline__ void operator()(const f32x4 (&acc)[2][2][4][2], const Unit& u, int wr, int wc, int fr, int fq) const {
;         int seqbase, t0, slen; halo_decode(u.pm, seqbase, t0, slen);
;         const f32x4* ct = (const f32x4*)(CT + (size_t)(128 * u.pn) * 8) + (32 * wc + 8 * fq) * 2;
;         const bool f0 = (fr == 0), f15 = (fr == 15);
; #pragma unroll
;         for (int ai = 0; ai < 2; ++ai) {
;             const int tbase = t0 + 62 * (2 * ai + wr) - 1;
;             float rs[4];
; #pragma unroll
;             for (int m = 0; m < 4; ++m) { const int t = tbase + 16 * m + fr; const bool vin = (t >= 0) && (t < slen); const int grow = seqbase + (vin ? t : 0);
;                 const f32x4 p = *(const f32x4*)(PS + (size_t)grow * 16 + 4 * fq); float s = (p[0] + p[1]) + (p[2] + p[3]); s = bfly_add<16>(s); s = bfly_add<32>(s); rs[m] = vin ? rsqrtf(s * (1.f / DM) + EPS) : 0.f; }
;             unsigned outw[4][2][2];
; #pragma unroll
;             for (int n = 0; n < 2; ++n)
; #pragma unroll
;                 for (int jp = 0; jp < 2; ++jp) {
;                     const int cidx = (4 * n + 2 * jp) * 2;
;                     const f32x4 c0a = ct[cidx], c0b = ct[cidx + 1], c1a = ct[cidx + 2], c1b = ct[cidx + 3];
;                     const f32x2 wv0 = {c0a[0], c1a[0]}, wv1 = {c0a[1], c1a[1]}, wv2 = {c0a[2], c1a[2]}, bv = {c0a[3], c1a[3]};
;                     const f32x2 wg0 = {c0b[0], c1b[0]}, wg1 = {c0b[1], c1b[1]}, wg2 = {c0b[2], c1b[2]}, bg = {c0b[3], c1b[3]};
;                     f32x2 uv[4], ug[4], cv[4];
; #pragma unroll
;                     for (int m = 0; m < 4; ++m) { uv[m] = (f32x2){acc[ai][0][m][n][2 * jp], acc[ai][0][m][n][2 * jp + 1]}; ug[m] = (f32x2){acc[ai][1][m][n][2 * jp], acc[ai][1][m][n][2 * jp + 1]}; }
;                     asm volatile("" : "+v"(uv[0]), "+v"(uv[1]), "+v"(uv[2]), "+v"(uv[3]), "+v"(ug[0]), "+v"(ug[1]), "+v"(ug[2]), "+v"(ug[3]));
;                     {
;                         f32x2 rv[4], lv[4];
; #pragma unroll
;                         for (int m = 0; m < 4; ++m) { uv[m] = uv[m] * rs[m]; rv[m] = (f32x2){dpp_ror1(uv[m][0]), dpp_ror1(uv[m][1])}; lv[m] = (f32x2){dpp_ror15(uv[m][0]), dpp_ror15(uv[m][1])}; }
; #pragma unroll
;                         for (int m = 0; m < 4; ++m) { const f32x2 pv_ = (m > 0 && f0) ? rv[m > 0 ? m - 1 : 0] : rv[m], nv_ = (m < 3 && f15) ? lv[m < 3 ? m + 1 : 3] : lv[m];
EC2_join:
	s_mul_i32 s86, s86, 0xf8
	s_bfe_u32 s89, s81, 0x10008
	s_mul_i32 s89, s89, 62
	s_add_i32 s89, s89, s86
	s_add_i32 s89, s89, -1
	v_readlane_b32 s64, v254, 0
	v_readlane_b32 s65, v254, 1
	v_readlane_b32 s66, v255, 4
	s_nop 2
	s_load_dwordx2 s[98:99], s[64:65], 0xe0
	s_mul_i32 s66, s66, 0x16000
	s_bfe_u32 s32, s81, 0x20006
	s_movk_i32 s54, 0x1600
	v_mbcnt_lo_u32_b32 v176, -1, 0
	v_mbcnt_hi_u32_b32 v176, -1, v176
	v_and_b32_e32 v170, 15, v176
	v_lshlrev_b32_e32 v170, 2, v170
	v_bfe_u32 v171, v176, 4, 2
	v_lshlrev_b32_e32 v172, 8, v171
	v_lshlrev_b32_e32 v171, 4, v171
	v_mov_b32_e32 v252, s78
	s_waitcnt lgkmcnt(0)
	s_lshl_b32 s51, s33, 12
	s_add_i32 s51, s51, s66
	s_lshl_b32 s52, s32, 10
	s_add_i32 s51, s51, s52
	s_add_i32 s51, s51, 0x3500000
	s_add_u32 s100, s98, s51
	s_addc_u32 s101, s99, 0
	s_add_u32 s70, s98, 0x3600000
	s_addc_u32 s71, s99, 0
	s_lshl_b32 s51, s33, 8
	s_lshl_b32 s52, s32, 6
	s_add_i32 s51, s51, s52
	s_add_i32 s51, s51, 0xf400000
	s_add_u32 s86, s98, s51
	s_addc_u32 s87, s99, 0
	v_add_u32_e32 v174, s89, v170
	v_add_u32_e32 v176, 0, v174
	v_cmp_gt_u32_e64 s[52:53], s91, v176
	s_nop 1
	v_cndmask_b32_e64 v176, 0, v176, s[52:53]
	v_add_u32_e32 v176, s88, v176
	v_lshl_add_u32 v248, v176, 6, v171
	global_load_dwordx4 v[222:225], v248, s[70:71]
	v_add_u32_e32 v176, 1, v174
	v_cmp_gt_u32_e64 s[64:65], s91, v176
	s_nop 1
	v_cndmask_b32_e64 v176, 0, v176, s[64:65]
	v_add_u32_e32 v176, s88, v176
	v_lshl_add_u32 v249, v176, 6, v171
	global_load_dwordx4 v[226:229], v249, s[70:71]
	v_add_u32_e32 v176, 2, v174
	v_cmp_gt_u32_e64 s[98:99], s91, v176
	s_nop 1
	v_cndmask_b32_e64 v176, 0, v176, s[98:99]
	v_add_u32_e32 v176, s88, v176
	v_lshl_add_u32 v250, v176, 6, v171
	global_load_dwordx4 v[230:233], v250, s[70:71]
	v_add_u32_e32 v176, 3, v174
	v_cmp_gt_u32_e64 s[32:33], s91, v176
	s_nop 1
	v_cndmask_b32_e64 v176, 0, v176, s[32:33]
	v_add_u32_e32 v176, s88, v176
	v_lshl_add_u32 v251, v176, 6, v171
	global_load_dwordx4 v[234:237], v251, s[70:71]
	global_load_dwordx4 v[190:193], v172, s[100:101]
	global_load_dwordx4 v[194:197], v172, s[100:101] offset:16
	global_load_dwordx4 v[198:201], v172, s[100:101] offset:32
	global_load_dwordx4 v[202:205], v172, s[100:101] offset:48
	s_waitcnt vmcnt(7)
	v_add_f32_e32 v222, v222, v223
	v_add_f32_e32 v224, v224, v225
	v_add_f32_e32 v222, v222, v224
	v_mov_b32_e32 v223, v222
	s_nop 1
	v_permlane16_swap_b32_e32 v222, v223
	v_add_f32_e32 v222, v222, v223
	v_mov_b32_e32 v223, v222
	s_nop 1
	v_permlane32_swap_b32_e32 v222, v223
	v_add_f32_e32 v222, v222, v223
	v_fma_f32 v222, v222, s82, v252
	v_rsq_f32_e32 v222, v222
	s_nop 0
	v_cndmask_b32_e64 v178, 0, v222, s[52:53]
	s_waitcnt vmcnt(6)
	v_add_f32_e32 v226, v226, v227
	v_add_f32_e32 v228, v228, v229
	v_add_f32_e32 v226, v226, v228
	v_mov_b32_e32 v227, v226
	s_nop 1
	v_permlane16_swap_b32_e32 v226, v227
	v_add_f32_e32 v226, v226, v227
	v_mov_b32_e32 v227, v226
	s_nop 1
	v_permlane32_swap_b32_e32 v226, v227
	v_add_f32_e32 v226, v226, v227
	v_fma_f32 v226, v226, s82, v252
	v_rsq_f32_e32 v226, v226
	s_nop 0
	v_cndmask_b32_e64 v180, 0, v226, s[64:65]
	s_waitcnt vmcnt(5)
	v_add_f32_e32 v230, v230, v231
	v_add_f32_e32 v232, v232, v233
	v_add_f32_e32 v230, v230, v232
	v_mov_b32_e32 v231, v230
	s_nop 1
	v_permlane16_swap_b32_e32 v230, v231
	v_add_f32_e32 v230, v230, v231
	v_mov_b32_e32 v231, v230
	s_nop 1
	v_permlane32_swap_b32_e32 v230, v231
	v_add_f32_e32 v230, v230, v231
	v_fma_f32 v230, v230, s82, v252
	v_rsq_f32_e32 v230, v230
	s_nop 0
	v_cndmask_b32_e64 v182, 0, v230, s[98:99]
	s_waitcnt vmcnt(4)
	v_add_f32_e32 v234, v234, v235
	v_add_f32_e32 v236, v236, v237
	v_add_f32_e32 v234, v234, v236
	v_mov_b32_e32 v235, v234
	s_nop 1
	v_permlane16_swap_b32_e32 v234, v235
	v_add_f32_e32 v234, v234, v235
	v_mov_b32_e32 v235, v234
	s_nop 1
	v_permlane32_swap_b32_e32 v234, v235
	v_add_f32_e32 v234, v234, v235
	v_fma_f32 v234, v234, s82, v252
	v_rsq_f32_e32 v234, v234
	s_nop 0
	v_cndmask_b32_e64 v144, 0, v234, s[32:33]
	global_load_dwordx4 v[206:209], v172, s[100:101] offset:64
	global_load_dwordx4 v[210:213], v172, s[100:101] offset:80
	global_load_dwordx4 v[214:217], v172, s[100:101] offset:96
	global_load_dwordx4 v[218:221], v172, s[100:101] offset:112
	s_waitcnt vmcnt(4)
	v_pk_mul_f32 v[124:125], v[124:125], v[178:179] op_sel_hi:[1,0]
	v_pk_mul_f32 v[120:121], v[120:121], v[180:181] op_sel_hi:[1,0]
	v_pk_mul_f32 v[116:117], v[116:117], v[182:183] op_sel_hi:[1,0]
	v_pk_mul_f32 v[112:113], v[112:113], v[144:145] op_sel_hi:[1,0]
	v_pk_mul_f32 v[108:109], v[108:109], v[178:179] op_sel_hi:[1,0]
	v_pk_mul_f32 v[104:105], v[104:105], v[180:181] op_sel_hi:[1,0]
	v_pk_mul_f32 v[100:101], v[100:101], v[182:183] op_sel_hi:[1,0]
	v_pk_mul_f32 v[96:97], v[96:97], v[144:145] op_sel_hi:[1,0]
	s_nop 1
	v_mov_b32_dpp v248, v112 row_shr:1 row_mask:0xf bank_mask:0xf bound_ctrl:1
	v_mov_b32_dpp v249, v113 row_shr:1 row_mask:0xf bank_mask:0xf bound_ctrl:1
	v_mov_b32_dpp v250, v124 row_shl:1 row_mask:0xf bank_mask:0xf bound_ctrl:1
	v_mov_b32_dpp v251, v125 row_shl:1 row_mask:0xf bank_mask:0xf bound_ctrl:1
	v_pk_fma_f32 v[224:225], v[190:191], v[248:249], v[196:197]
	v_pk_fma_f32 v[226:227], v[190:191], v[124:125], v[196:197]
	v_pk_fma_f32 v[228:229], v[190:191], v[120:121], v[196:197]
	v_pk_fma_f32 v[230:231], v[190:191], v[116:117], v[196:197]
	v_pk_fma_f32 v[224:225], v[192:193], v[124:125], v[224:225]
	v_pk_fma_f32 v[226:227], v[192:193], v[120:121], v[226:227]
	v_pk_fma_f32 v[228:229], v[192:193], v[116:117], v[228:229]
	v_pk_fma_f32 v[230:231], v[192:193], v[112:113], v[230:231]
	v_pk_fma_f32 v[224:225], v[194:195], v[120:121], v[224:225]
	v_pk_fma_f32 v[226:227], v[194:195], v[116:117], v[226:227]
; __device__ __forceinline__ unsigned cvtpk(float lo, float hi) { f32x2 v = {lo, hi}; bf16x2_t b = __builtin_convertvector(v, bf16x2_t); return __builtin_bit_cast(unsigned, b); }
; __device__ __forceinline__ float dpp_ror1(float x) { return __builtin_bit_cast(float, __builtin_amdgcn_mov_dpp(__builtin_bit_cast(int, x), 0x121, 0xF, 0xF, true)); }
; __device__ __forceinline__ float dpp_ror15(float x) { return __builtin_bit_cast(float, __builtin_amdgcn_mov_dpp(__builtin_bit_cast(int, x), 0x12F, 0xF, 0xF, true)); }
;     __device__ __forceinline__ void operator()(const f32x4 (&acc)[2][2][4][2], const Unit& u, int wr, int wc, int fr, int fq) const {
;     ...
;                         for (int m = 0; m < 4; ++m) { uv[m] = uv[m] * rs[m]; rv[m] = (f32x2){dpp_ror1(uv[m][0]), dpp_ror1(uv[m][1])}; lv[m] = (f32x2){dpp_ror15(uv[m][0]), dpp_ror15(uv[m][1])}; }
; #pragma unroll
;                         for (int m = 0; m < 4; ++m) { const f32x2 pv_ = (m > 0 && f0) ? rv[m > 0 ? m - 1 : 0] : rv[m], nv_ = (m < 3 && f15) ? lv[m < 3 ? m + 1 : 3] : lv[m];
;                             cv[m] = bv + wv0 * pv_ + wv1 * uv[m] + wv2 * nv_; }
;                     }
;                     asm volatile("" : "+v"(cv[0]), "+v"(cv[1]), "+v"(cv[2]), "+v"(cv[3]));
;                     {
;                         f32x2 rg[4], lg[4];
; #pragma unroll
;                         for (int m = 0; m < 4; ++m) { ug[m] = ug[m] * rs[m]; rg[m] = (f32x2){dpp_ror1(ug[m][0]), dpp_ror1(ug[m][1])}; lg[m] = (f32x2){dpp_ror15(ug[m][0]), dpp_ror15(ug[m][1])}; }
; #pragma unroll
;                         for (int m = 0; m < 4; ++m) { const f32x2 pg_ = (m > 0 && f0) ? rg[m > 0 ? m - 1 : 0] : rg[m], ng_ = (m < 3 && f15) ? lg[m < 3 ? m + 1 : 3] : lg[m];
;                             const f32x2 cgt = bg + wg0 * pg_ + wg1 * ug[m] + wg2 * ng_;
;                             const f32x2 e = cgt * (-LOG2E);
;                             const f32x2 d = (f32x2){__builtin_amdgcn_exp2f(e[0]), __builtin_amdgcn_exp2f(e[1])} + 1.f;
;                             const f32x2 sg = {__builtin_amdgcn_rcpf(d[0]), __builtin_amdgcn_rcpf(d[1])};
;                             const f32x2 ov = cv[m] * cgt * sg;
;                             outw[m][n][jp] = cvtpk(ov[0], ov[1]); }
	v_pk_fma_f32 v[228:229], v[194:195], v[112:113], v[228:229]
	v_pk_fma_f32 v[230:231], v[194:195], v[250:251], v[230:231]
	s_nop 1
	v_mov_b32_dpp v248, v96 row_shr:1 row_mask:0xf bank_mask:0xf bound_ctrl:1
	v_mov_b32_dpp v249, v97 row_shr:1 row_mask:0xf bank_mask:0xf bound_ctrl:1
	v_mov_b32_dpp v250, v108 row_shl:1 row_mask:0xf bank_mask:0xf bound_ctrl:1
	v_mov_b32_dpp v251, v109 row_shl:1 row_mask:0xf bank_mask:0xf bound_ctrl:1
	v_pk_fma_f32 v[232:233], v[198:199], v[248:249], v[204:205]
	v_pk_fma_f32 v[234:235], v[198:199], v[108:109], v[204:205]
	v_pk_fma_f32 v[236:237], v[198:199], v[104:105], v[204:205]
	v_pk_fma_f32 v[238:239], v[198:199], v[100:101], v[204:205]
	v_pk_fma_f32 v[232:233], v[200:201], v[108:109], v[232:233]
	v_pk_fma_f32 v[234:235], v[200:201], v[104:105], v[234:235]
	v_pk_fma_f32 v[236:237], v[200:201], v[100:101], v[236:237]
	v_pk_fma_f32 v[238:239], v[200:201], v[96:97], v[238:239]
	v_pk_fma_f32 v[232:233], v[202:203], v[104:105], v[232:233]
	v_pk_fma_f32 v[234:235], v[202:203], v[100:101], v[234:235]
	v_pk_fma_f32 v[236:237], v[202:203], v[96:97], v[236:237]
	v_pk_fma_f32 v[238:239], v[202:203], v[250:251], v[238:239]
	v_exp_f32_e64 v240, -v232
	v_exp_f32_e64 v241, -v233
	v_exp_f32_e64 v242, -v234
	v_exp_f32_e64 v243, -v235
	v_exp_f32_e64 v244, -v236
	v_exp_f32_e64 v245, -v237
	v_exp_f32_e64 v246, -v238
	v_exp_f32_e64 v247, -v239
	v_pk_mul_f32 v[224:225], v[224:225], v[232:233]
	v_pk_mul_f32 v[226:227], v[226:227], v[234:235]
	v_pk_mul_f32 v[228:229], v[228:229], v[236:237]
	v_pk_mul_f32 v[230:231], v[230:231], v[238:239]
	v_pk_add_f32 v[240:241], v[240:241], 1.0 op_sel_hi:[1,0]
	v_pk_add_f32 v[242:243], v[242:243], 1.0 op_sel_hi:[1,0]
	v_pk_add_f32 v[244:245], v[244:245], 1.0 op_sel_hi:[1,0]
	v_pk_add_f32 v[246:247], v[246:247], 1.0 op_sel_hi:[1,0]
	v_rcp_f32_e32 v240, v240
	v_rcp_f32_e32 v241, v241
	v_rcp_f32_e32 v242, v242
	v_rcp_f32_e32 v243, v243
	v_rcp_f32_e32 v244, v244
	v_rcp_f32_e32 v245, v245
	v_rcp_f32_e32 v246, v246
	v_rcp_f32_e32 v247, v247
	s_nop 0
	v_pk_mul_f32 v[224:225], v[224:225], v[240:241]
	v_pk_mul_f32 v[226:227], v[226:227], v[242:243]
	v_pk_mul_f32 v[228:229], v[228:229], v[244:245]
	v_pk_mul_f32 v[230:231], v[230:231], v[246:247]
	v_cvt_pk_bf16_f32 v128, v224, v225
	v_cvt_pk_bf16_f32 v132, v226, v227
	v_cvt_pk_bf16_f32 v136, v228, v229
	v_cvt_pk_bf16_f32 v140, v230, v231
	global_load_dwordx4 v[190:193], v172, s[100:101] offset:128
	global_load_dwordx4 v[194:197], v172, s[100:101] offset:144
	global_load_dwordx4 v[198:201], v172, s[100:101] offset:160
	global_load_dwordx4 v[202:205], v172, s[100:101] offset:176
	s_waitcnt vmcnt(4)
	v_pk_mul_f32 v[126:127], v[126:127], v[178:179] op_sel_hi:[1,0]
	v_pk_mul_f32 v[122:123], v[122:123], v[180:181] op_sel_hi:[1,0]
	v_pk_mul_f32 v[118:119], v[118:119], v[182:183] op_sel_hi:[1,0]
	v_pk_mul_f32 v[114:115], v[114:115], v[144:145] op_sel_hi:[1,0]
	v_pk_mul_f32 v[110:111], v[110:111], v[178:179] op_sel_hi:[1,0]
	v_pk_mul_f32 v[106:107], v[106:107], v[180:181] op_sel_hi:[1,0]
	v_pk_mul_f32 v[102:103], v[102:103], v[182:183] op_sel_hi:[1,0]
	v_pk_mul_f32 v[98:99], v[98:99], v[144:145] op_sel_hi:[1,0]
	s_nop 1
	v_mov_b32_dpp v248, v114 row_shr:1 row_mask:0xf bank_mask:0xf bound_ctrl:1
	v_mov_b32_dpp v249, v115 row_shr:1 row_mask:0xf bank_mask:0xf bound_ctrl:1
	v_mov_b32_dpp v250, v126 row_shl:1 row_mask:0xf bank_mask:0xf bound_ctrl:1
	v_mov_b32_dpp v251, v127 row_shl:1 row_mask:0xf bank_mask:0xf bound_ctrl:1
	v_pk_fma_f32 v[224:225], v[206:207], v[248:249], v[212:213]
	v_pk_fma_f32 v[226:227], v[206:207], v[126:127], v[212:213]
	v_pk_fma_f32 v[228:229], v[206:207], v[122:123], v[212:213]
	v_pk_fma_f32 v[230:231], v[206:207], v[118:119], v[212:213]
	v_pk_fma_f32 v[224:225], v[208:209], v[126:127], v[224:225]
	v_pk_fma_f32 v[226:227], v[208:209], v[122:123], v[226:227]
	v_pk_fma_f32 v[228:229], v[208:209], v[118:119], v[228:229]
	v_pk_fma_f32 v[230:231], v[208:209], v[114:115], v[230:231]
	v_pk_fma_f32 v[224:225], v[210:211], v[122:123], v[224:225]
	v_pk_fma_f32 v[226:227], v[210:211], v[118:119], v[226:227]
	v_pk_fma_f32 v[228:229], v[210:211], v[114:115], v[228:229]
	v_pk_fma_f32 v[230:231], v[210:211], v[250:251], v[230:231]
	s_nop 1
	v_mov_b32_dpp v248, v98 row_shr:1 row_mask:0xf bank_mask:0xf bound_ctrl:1
	v_mov_b32_dpp v249, v99 row_shr:1 row_mask:0xf bank_mask:0xf bound_ctrl:1
	v_mov_b32_dpp v250, v110 row_shl:1 row_mask:0xf bank_mask:0xf bound_ctrl:1
	v_mov_b32_dpp v251, v111 row_shl:1 row_mask:0xf bank_mask:0xf bound_ctrl:1
	v_pk_fma_f32 v[232:233], v[214:215], v[248:249], v[220:221]
	v_pk_fma_f32 v[234:235], v[214:215], v[110:111], v[220:221]
	v_pk_fma_f32 v[236:237], v[214:215], v[106:107], v[220:221]
	v_pk_fma_f32 v[238:239], v[214:215], v[102:103], v[220:221]
	v_pk_fma_f32 v[232:233], v[216:217], v[110:111], v[232:233]
	v_pk_fma_f32 v[234:235], v[216:217], v[106:107], v[234:235]
	v_pk_fma_f32 v[236:237], v[216:217], v[102:103], v[236:237]
	v_pk_fma_f32 v[238:239], v[216:217], v[98:99], v[238:239]
	v_pk_fma_f32 v[232:233], v[218:219], v[106:107], v[232:233]
	v_pk_fma_f32 v[234:235], v[218:219], v[102:103], v[234:235]
	v_pk_fma_f32 v[236:237], v[218:219], v[98:99], v[236:237]
	v_pk_fma_f32 v[238:239], v[218:219], v[250:251], v[238:239]
	v_exp_f32_e64 v240, -v232
	v_exp_f32_e64 v241, -v233
	v_exp_f32_e64 v242, -v234
	v_exp_f32_e64 v243, -v235
	v_exp_f32_e64 v244, -v236
	v_exp_f32_e64 v245, -v237
	v_exp_f32_e64 v246, -v238
	v_exp_f32_e64 v247, -v239
	v_pk_mul_f32 v[224:225], v[224:225], v[232:233]
	v_pk_mul_f32 v[226:227], v[226:227], v[234:235]
	v_pk_mul_f32 v[228:229], v[228:229], v[236:237]
	v_pk_mul_f32 v[230:231], v[230:231], v[238:239]
	v_pk_add_f32 v[240:241], v[240:241], 1.0 op_sel_hi:[1,0]
	v_pk_add_f32 v[242:243], v[242:243], 1.0 op_sel_hi:[1,0]
	v_pk_add_f32 v[244:245], v[244:245], 1.0 op_sel_hi:[1,0]
	v_pk_add_f32 v[246:247], v[246:247], 1.0 op_sel_hi:[1,0]
	v_rcp_f32_e32 v240, v240
	v_rcp_f32_e32 v241, v241
	v_rcp_f32_e32 v242, v242
	v_rcp_f32_e32 v243, v243
	v_rcp_f32_e32 v244, v244
	v_rcp_f32_e32 v245, v245
	v_rcp_f32_e32 v246, v246
	v_rcp_f32_e32 v247, v247
	s_nop 0
	v_pk_mul_f32 v[224:225], v[224:225], v[240:241]
	v_pk_mul_f32 v[226:227], v[226:227], v[242:243]
	v_pk_mul_f32 v[228:229], v[228:229], v[244:245]
	v_pk_mul_f32 v[230:231], v[230:231], v[246:247]
	v_cvt_pk_bf16_f32 v129, v224, v225
	v_cvt_pk_bf16_f32 v133, v226, v227
	v_cvt_pk_bf16_f32 v137, v228, v229
	v_cvt_pk_bf16_f32 v141, v230, v231
	global_load_dwordx4 v[206:209], v172, s[100:101] offset:192
	global_load_dwordx4 v[210:213], v172, s[100:101] offset:208
	global_load_dwordx4 v[214:217], v172, s[100:101] offset:224
	global_load_dwordx4 v[218:221], v172, s[100:101] offset:240
	s_waitcnt vmcnt(4)
; __device__ __forceinline__ unsigned cvtpk(float lo, float hi) { f32x2 v = {lo, hi}; bf16x2_t b = __builtin_convertvector(v, bf16x2_t); return __builtin_bit_cast(unsigned, b); }
;     __device__ __forceinline__ void operator()(const f32x4 (&acc)[2][2][4][2], const Unit& u, int wr, int wc, int fr, int fq) const {
;     ...
;             const int tbase = t0 + 62 * (2 * ai + wr) - 1;
;             float rs[4];
; #pragma unroll
;             for (int m = 0; m < 4; ++m) { const int t = tbase + 16 * m + fr; const bool vin = (t >= 0) && (t < slen); const int grow = seqbase + (vin ? t : 0);
;                 const f32x4 p = *(const f32x4*)(PS + (size_t)grow * 16 + 4 * fq); float s = (p[0] + p[1]) + (p[2] + p[3]); s = bfly_add<16>(s); s = bfly_add<32>(s); rs[m] = vin ? rsqrtf(s * (1.f / DM) + EPS) : 0.f; }
;     ...
;                         for (int m = 0; m < 4; ++m) { uv[m] = uv[m] * rs[m]; rv[m] = (f32x2){dpp_ror1(uv[m][0]), dpp_ror1(uv[m][1])}; lv[m] = (f32x2){dpp_ror15(uv[m][0]), dpp_ror15(uv[m][1])}; }
; #pragma unroll
;                         for (int m = 0; m < 4; ++m) { const f32x2 pv_ = (m > 0 && f0) ? rv[m > 0 ? m - 1 : 0] : rv[m], nv_ = (m < 3 && f15) ? lv[m < 3 ? m + 1 : 3] : lv[m];
;                             cv[m] = bv + wv0 * pv_ + wv1 * uv[m] + wv2 * nv_; }
;                     }
;                     asm volatile("" : "+v"(cv[0]), "+v"(cv[1]), "+v"(cv[2]), "+v"(cv[3]));
;                     {
;                         f32x2 rg[4], lg[4];
; #pragma unroll
;                         for (int m = 0; m < 4; ++m) { ug[m] = ug[m] * rs[m]; rg[m] = (f32x2){dpp_ror1(ug[m][0]), dpp_ror1(ug[m][1])}; lg[m] = (f32x2){dpp_ror15(ug[m][0]), dpp_ror15(ug[m][1])}; }
; #pragma unroll
;                         for (int m = 0; m < 4; ++m) { const f32x2 pg_ = (m > 0 && f0) ? rg[m > 0 ? m - 1 : 0] : rg[m], ng_ = (m < 3 && f15) ? lg[m < 3 ? m + 1 : 3] : lg[m];
;                             const f32x2 cgt = bg + wg0 * pg_ + wg1 * ug[m] + wg2 * ng_;
;                             const f32x2 e = cgt * (-LOG2E);
;                             const f32x2 d = (f32x2){__builtin_amdgcn_exp2f(e[0]), __builtin_amdgcn_exp2f(e[1])} + 1.f;
;                             const f32x2 sg = {__builtin_amdgcn_rcpf(d[0]), __builtin_amdgcn_rcpf(d[1])};
;                             const f32x2 ov = cv[m] * cgt * sg;
;                             outw[m][n][jp] = cvtpk(ov[0], ov[1]); }
	v_pk_mul_f32 v[92:93], v[92:93], v[178:179] op_sel_hi:[1,0]
	v_pk_mul_f32 v[88:89], v[88:89], v[180:181] op_sel_hi:[1,0]
	v_pk_mul_f32 v[84:85], v[84:85], v[182:183] op_sel_hi:[1,0]
	v_pk_mul_f32 v[80:81], v[80:81], v[144:145] op_sel_hi:[1,0]
	v_pk_mul_f32 v[76:77], v[76:77], v[178:179] op_sel_hi:[1,0]
	v_pk_mul_f32 v[72:73], v[72:73], v[180:181] op_sel_hi:[1,0]
	v_pk_mul_f32 v[68:69], v[68:69], v[182:183] op_sel_hi:[1,0]
	v_pk_mul_f32 v[64:65], v[64:65], v[144:145] op_sel_hi:[1,0]
	s_nop 1
	v_mov_b32_dpp v248, v80 row_shr:1 row_mask:0xf bank_mask:0xf bound_ctrl:1
	v_mov_b32_dpp v249, v81 row_shr:1 row_mask:0xf bank_mask:0xf bound_ctrl:1
	v_mov_b32_dpp v250, v92 row_shl:1 row_mask:0xf bank_mask:0xf bound_ctrl:1
	v_mov_b32_dpp v251, v93 row_shl:1 row_mask:0xf bank_mask:0xf bound_ctrl:1
	v_pk_fma_f32 v[224:225], v[190:191], v[248:249], v[196:197]
	v_pk_fma_f32 v[226:227], v[190:191], v[92:93], v[196:197]
	v_pk_fma_f32 v[228:229], v[190:191], v[88:89], v[196:197]
	v_pk_fma_f32 v[230:231], v[190:191], v[84:85], v[196:197]
	v_pk_fma_f32 v[224:225], v[192:193], v[92:93], v[224:225]
	v_pk_fma_f32 v[226:227], v[192:193], v[88:89], v[226:227]
	v_pk_fma_f32 v[228:229], v[192:193], v[84:85], v[228:229]
	v_pk_fma_f32 v[230:231], v[192:193], v[80:81], v[230:231]
	v_pk_fma_f32 v[224:225], v[194:195], v[88:89], v[224:225]
	v_pk_fma_f32 v[226:227], v[194:195], v[84:85], v[226:227]
	v_pk_fma_f32 v[228:229], v[194:195], v[80:81], v[228:229]
	v_pk_fma_f32 v[230:231], v[194:195], v[250:251], v[230:231]
	s_nop 1
	v_mov_b32_dpp v248, v64 row_shr:1 row_mask:0xf bank_mask:0xf bound_ctrl:1
	v_mov_b32_dpp v249, v65 row_shr:1 row_mask:0xf bank_mask:0xf bound_ctrl:1
	v_mov_b32_dpp v250, v76 row_shl:1 row_mask:0xf bank_mask:0xf bound_ctrl:1
	v_mov_b32_dpp v251, v77 row_shl:1 row_mask:0xf bank_mask:0xf bound_ctrl:1
	v_pk_fma_f32 v[232:233], v[198:199], v[248:249], v[204:205]
	v_pk_fma_f32 v[234:235], v[198:199], v[76:77], v[204:205]
	v_pk_fma_f32 v[236:237], v[198:199], v[72:73], v[204:205]
	v_pk_fma_f32 v[238:239], v[198:199], v[68:69], v[204:205]
	v_pk_fma_f32 v[232:233], v[200:201], v[76:77], v[232:233]
	v_pk_fma_f32 v[234:235], v[200:201], v[72:73], v[234:235]
	v_pk_fma_f32 v[236:237], v[200:201], v[68:69], v[236:237]
	v_pk_fma_f32 v[238:239], v[200:201], v[64:65], v[238:239]
	v_pk_fma_f32 v[232:233], v[202:203], v[72:73], v[232:233]
	v_pk_fma_f32 v[234:235], v[202:203], v[68:69], v[234:235]
	v_pk_fma_f32 v[236:237], v[202:203], v[64:65], v[236:237]
	v_pk_fma_f32 v[238:239], v[202:203], v[250:251], v[238:239]
	v_exp_f32_e64 v240, -v232
	v_exp_f32_e64 v241, -v233
	v_exp_f32_e64 v242, -v234
	v_exp_f32_e64 v243, -v235
	v_exp_f32_e64 v244, -v236
	v_exp_f32_e64 v245, -v237
	v_exp_f32_e64 v246, -v238
	v_exp_f32_e64 v247, -v239
	v_pk_mul_f32 v[224:225], v[224:225], v[232:233]
	v_pk_mul_f32 v[226:227], v[226:227], v[234:235]
	v_pk_mul_f32 v[228:229], v[228:229], v[236:237]
	v_pk_mul_f32 v[230:231], v[230:231], v[238:239]
	v_pk_add_f32 v[240:241], v[240:241], 1.0 op_sel_hi:[1,0]
	v_pk_add_f32 v[242:243], v[242:243], 1.0 op_sel_hi:[1,0]
	v_pk_add_f32 v[244:245], v[244:245], 1.0 op_sel_hi:[1,0]
	v_pk_add_f32 v[246:247], v[246:247], 1.0 op_sel_hi:[1,0]
	v_rcp_f32_e32 v240, v240
	v_rcp_f32_e32 v241, v241
	v_rcp_f32_e32 v242, v242
	v_rcp_f32_e32 v243, v243
	v_rcp_f32_e32 v244, v244
	v_rcp_f32_e32 v245, v245
	v_rcp_f32_e32 v246, v246
	v_rcp_f32_e32 v247, v247
	s_nop 0
	v_pk_mul_f32 v[224:225], v[224:225], v[240:241]
	v_pk_mul_f32 v[226:227], v[226:227], v[242:243]
	v_pk_mul_f32 v[228:229], v[228:229], v[244:245]
	v_pk_mul_f32 v[230:231], v[230:231], v[246:247]
	v_cvt_pk_bf16_f32 v130, v224, v225
	v_cvt_pk_bf16_f32 v134, v226, v227
	v_cvt_pk_bf16_f32 v138, v228, v229
	v_cvt_pk_bf16_f32 v142, v230, v231
	s_waitcnt vmcnt(0)
	v_add_u32_e32 v253, 0x7c, v174
	v_add_u32_e32 v176, 0, v253
	v_cmp_gt_u32_e64 s[52:53], s91, v176
	s_nop 1
	v_cndmask_b32_e64 v176, 0, v176, s[52:53]
	v_add_u32_e32 v176, s88, v176
	v_lshl_add_u32 v248, v176, 6, v171
	global_load_dwordx4 v[190:193], v248, s[70:71]
	v_add_u32_e32 v176, 1, v253
	v_cmp_gt_u32_e64 s[64:65], s91, v176
	s_nop 1
	v_cndmask_b32_e64 v176, 0, v176, s[64:65]
	v_add_u32_e32 v176, s88, v176
	v_lshl_add_u32 v249, v176, 6, v171
	global_load_dwordx4 v[194:197], v249, s[70:71]
	v_add_u32_e32 v176, 2, v253
	v_cmp_gt_u32_e64 s[98:99], s91, v176
	s_nop 1
	v_cndmask_b32_e64 v176, 0, v176, s[98:99]
	v_add_u32_e32 v176, s88, v176
	v_lshl_add_u32 v250, v176, 6, v171
	global_load_dwordx4 v[198:201], v250, s[70:71]
	v_add_u32_e32 v176, 3, v253
	v_cmp_gt_u32_e64 s[32:33], s91, v176
	s_nop 1
	v_cndmask_b32_e64 v176, 0, v176, s[32:33]
	v_add_u32_e32 v176, s88, v176
	v_lshl_add_u32 v251, v176, 6, v171
	global_load_dwordx4 v[202:205], v251, s[70:71]
	v_pk_mul_f32 v[94:95], v[94:95], v[178:179] op_sel_hi:[1,0]
	v_pk_mul_f32 v[90:91], v[90:91], v[180:181] op_sel_hi:[1,0]
	v_pk_mul_f32 v[86:87], v[86:87], v[182:183] op_sel_hi:[1,0]
	v_pk_mul_f32 v[82:83], v[82:83], v[144:145] op_sel_hi:[1,0]
	v_pk_mul_f32 v[78:79], v[78:79], v[178:179] op_sel_hi:[1,0]
	v_pk_mul_f32 v[74:75], v[74:75], v[180:181] op_sel_hi:[1,0]
	v_pk_mul_f32 v[70:71], v[70:71], v[182:183] op_sel_hi:[1,0]
	v_pk_mul_f32 v[66:67], v[66:67], v[144:145] op_sel_hi:[1,0]
	s_nop 1
	v_mov_b32_dpp v248, v82 row_shr:1 row_mask:0xf bank_mask:0xf bound_ctrl:1
	v_mov_b32_dpp v249, v83 row_shr:1 row_mask:0xf bank_mask:0xf bound_ctrl:1
	v_mov_b32_dpp v250, v94 row_shl:1 row_mask:0xf bank_mask:0xf bound_ctrl:1
	v_mov_b32_dpp v251, v95 row_shl:1 row_mask:0xf bank_mask:0xf bound_ctrl:1
	v_pk_fma_f32 v[224:225], v[206:207], v[248:249], v[212:213]
	v_pk_fma_f32 v[226:227], v[206:207], v[94:95], v[212:213]
; __device__ __forceinline__ unsigned cvtpk(float lo, float hi) { f32x2 v = {lo, hi}; bf16x2_t b = __builtin_convertvector(v, bf16x2_t); return __builtin_bit_cast(unsigned, b); }
;     __device__ __forceinline__ void operator()(const f32x4 (&acc)[2][2][4][2], const Unit& u, int wr, int wc, int fr, int fq) const {
;     ...
;             const int tbase = t0 + 62 * (2 * ai + wr) - 1;
;             float rs[4];
; #pragma unroll
;             for (int m = 0; m < 4; ++m) { const int t = tbase + 16 * m + fr; const bool vin = (t >= 0) && (t < slen); const int grow = seqbase + (vin ? t : 0);
;                 const f32x4 p = *(const f32x4*)(PS + (size_t)grow * 16 + 4 * fq); float s = (p[0] + p[1]) + (p[2] + p[3]); s = bfly_add<16>(s); s = bfly_add<32>(s); rs[m] = vin ? rsqrtf(s * (1.f / DM) + EPS) : 0.f; }
;     ...
;                         for (int m = 0; m < 4; ++m) { ug[m] = ug[m] * rs[m]; rg[m] = (f32x2){dpp_ror1(ug[m][0]), dpp_ror1(ug[m][1])}; lg[m] = (f32x2){dpp_ror15(ug[m][0]), dpp_ror15(ug[m][1])}; }
; #pragma unroll
;                         for (int m = 0; m < 4; ++m) { const f32x2 pg_ = (m > 0 && f0) ? rg[m > 0 ? m - 1 : 0] : rg[m], ng_ = (m < 3 && f15) ? lg[m < 3 ? m + 1 : 3] : lg[m];
;                             const f32x2 cgt = bg + wg0 * pg_ + wg1 * ug[m] + wg2 * ng_;
;                             const f32x2 e = cgt * (-LOG2E);
;                             const f32x2 d = (f32x2){__builtin_amdgcn_exp2f(e[0]), __builtin_amdgcn_exp2f(e[1])} + 1.f;
;                             const f32x2 sg = {__builtin_amdgcn_rcpf(d[0]), __builtin_amdgcn_rcpf(d[1])};
;                             const f32x2 ov = cv[m] * cgt * sg;
;                             outw[m][n][jp] = cvtpk(ov[0], ov[1]); }
;                     }
;                     asm volatile("" : "+v"(outw[0][n][jp]), "+v"(outw[1][n][jp]), "+v"(outw[2][n][jp]), "+v"(outw[3][n][jp]) :: "memory"); __builtin_amdgcn_sched_barrier(0);
;                 }
; #pragma unroll
;             for (int m = 0; m < 4; ++m) { const int i = 16 * m + fr, t = tbase + i;
;                 if (i >= 1 && i <= 62 && t < slen) { u32x4 w; w.x = outw[m][0][0]; w.y = outw[m][0][1]; w.z = outw[m][1][0]; w.w = outw[m][1][1];
;                     *(u32x4*)(Gout + (size_t)(seqbase + t) * DFF + 128 * u.pn + 32 * wc + 8 * fq) = w; } }
	v_pk_fma_f32 v[228:229], v[206:207], v[90:91], v[212:213]
	v_pk_fma_f32 v[230:231], v[206:207], v[86:87], v[212:213]
	v_pk_fma_f32 v[224:225], v[208:209], v[94:95], v[224:225]
	v_pk_fma_f32 v[226:227], v[208:209], v[90:91], v[226:227]
	v_pk_fma_f32 v[228:229], v[208:209], v[86:87], v[228:229]
	v_pk_fma_f32 v[230:231], v[208:209], v[82:83], v[230:231]
	v_pk_fma_f32 v[224:225], v[210:211], v[90:91], v[224:225]
	v_pk_fma_f32 v[226:227], v[210:211], v[86:87], v[226:227]
	v_pk_fma_f32 v[228:229], v[210:211], v[82:83], v[228:229]
	v_pk_fma_f32 v[230:231], v[210:211], v[250:251], v[230:231]
	s_nop 1
	v_mov_b32_dpp v248, v66 row_shr:1 row_mask:0xf bank_mask:0xf bound_ctrl:1
	v_mov_b32_dpp v249, v67 row_shr:1 row_mask:0xf bank_mask:0xf bound_ctrl:1
	v_mov_b32_dpp v250, v78 row_shl:1 row_mask:0xf bank_mask:0xf bound_ctrl:1
	v_mov_b32_dpp v251, v79 row_shl:1 row_mask:0xf bank_mask:0xf bound_ctrl:1
	v_pk_fma_f32 v[232:233], v[214:215], v[248:249], v[220:221]
	v_pk_fma_f32 v[234:235], v[214:215], v[78:79], v[220:221]
	v_pk_fma_f32 v[236:237], v[214:215], v[74:75], v[220:221]
	v_pk_fma_f32 v[238:239], v[214:215], v[70:71], v[220:221]
	v_pk_fma_f32 v[232:233], v[216:217], v[78:79], v[232:233]
	v_pk_fma_f32 v[234:235], v[216:217], v[74:75], v[234:235]
	v_pk_fma_f32 v[236:237], v[216:217], v[70:71], v[236:237]
	v_pk_fma_f32 v[238:239], v[216:217], v[66:67], v[238:239]
	v_pk_fma_f32 v[232:233], v[218:219], v[74:75], v[232:233]
	v_pk_fma_f32 v[234:235], v[218:219], v[70:71], v[234:235]
	v_pk_fma_f32 v[236:237], v[218:219], v[66:67], v[236:237]
	v_pk_fma_f32 v[238:239], v[218:219], v[250:251], v[238:239]
	v_exp_f32_e64 v240, -v232
	v_exp_f32_e64 v241, -v233
	v_exp_f32_e64 v242, -v234
	v_exp_f32_e64 v243, -v235
	v_exp_f32_e64 v244, -v236
	v_exp_f32_e64 v245, -v237
	v_exp_f32_e64 v246, -v238
	v_exp_f32_e64 v247, -v239
	v_pk_mul_f32 v[224:225], v[224:225], v[232:233]
	v_pk_mul_f32 v[226:227], v[226:227], v[234:235]
	v_pk_mul_f32 v[228:229], v[228:229], v[236:237]
	v_pk_mul_f32 v[230:231], v[230:231], v[238:239]
	v_pk_add_f32 v[240:241], v[240:241], 1.0 op_sel_hi:[1,0]
	v_pk_add_f32 v[242:243], v[242:243], 1.0 op_sel_hi:[1,0]
	v_pk_add_f32 v[244:245], v[244:245], 1.0 op_sel_hi:[1,0]
	v_pk_add_f32 v[246:247], v[246:247], 1.0 op_sel_hi:[1,0]
	v_rcp_f32_e32 v240, v240
	v_rcp_f32_e32 v241, v241
	v_rcp_f32_e32 v242, v242
	v_rcp_f32_e32 v243, v243
	v_rcp_f32_e32 v244, v244
	v_rcp_f32_e32 v245, v245
	v_rcp_f32_e32 v246, v246
	v_rcp_f32_e32 v247, v247
	s_nop 0
	v_pk_mul_f32 v[224:225], v[224:225], v[240:241]
	v_pk_mul_f32 v[226:227], v[226:227], v[242:243]
	v_pk_mul_f32 v[228:229], v[228:229], v[244:245]
	v_pk_mul_f32 v[230:231], v[230:231], v[246:247]
	v_cvt_pk_bf16_f32 v131, v224, v225
	v_cvt_pk_bf16_f32 v135, v226, v227
	v_cvt_pk_bf16_f32 v139, v228, v229
	v_cvt_pk_bf16_f32 v143, v230, v231
	s_sub_i32 s51, s91, s89
	s_sub_i32 s66, s51, 4
	s_max_i32 s66, s66, 0
	v_add_u32_e32 v176, -4, v170
	v_cmp_gt_u32_e32 vcc, s66, v176
	v_add_u32_e32 v176, 0, v174
	v_add_u32_e32 v176, s88, v176
	v_mad_u32_u24 v248, v176, s54, v171
	s_mov_b64 exec, vcc
	global_store_dwordx4 v248, v[128:131], s[86:87]
	s_mov_b64 exec, -1
	s_sub_i32 s66, s51, 1
	s_max_i32 s66, s66, 0
	v_cmp_gt_u32_e32 vcc, s66, v170
	v_add_u32_e32 v176, 1, v174
	v_add_u32_e32 v176, s88, v176
	v_mad_u32_u24 v249, v176, s54, v171
	s_mov_b64 exec, vcc
	global_store_dwordx4 v249, v[132:135], s[86:87]
	s_mov_b64 exec, -1
	s_sub_i32 s66, s51, 2
	s_max_i32 s66, s66, 0
	v_cmp_gt_u32_e32 vcc, s66, v170
	v_add_u32_e32 v176, 2, v174
	v_add_u32_e32 v176, s88, v176
	v_mad_u32_u24 v250, v176, s54, v171
	s_mov_b64 exec, vcc
	global_store_dwordx4 v250, v[136:139], s[86:87]
	s_mov_b64 exec, -1
	s_sub_i32 s66, s51, 3
	s_min_i32 s66, s66, 60
	s_max_i32 s66, s66, 0
	v_cmp_gt_u32_e32 vcc, s66, v170
	v_add_u32_e32 v176, 3, v174
	v_add_u32_e32 v176, s88, v176
	v_mad_u32_u24 v251, v176, s54, v171
	s_mov_b64 exec, vcc
	global_store_dwordx4 v251, v[140:143], s[86:87]
	s_mov_b64 exec, -1
	s_addk_i32 s89, 0x7c
	v_mov_b32_e32 v174, v253
	global_load_dwordx4 v[206:209], v172, s[100:101]
	global_load_dwordx4 v[210:213], v172, s[100:101] offset:16
	global_load_dwordx4 v[214:217], v172, s[100:101] offset:32
	global_load_dwordx4 v[218:221], v172, s[100:101] offset:48
	s_waitcnt vmcnt(11)
	v_add_f32_e32 v190, v190, v191
	v_add_f32_e32 v192, v192, v193
	v_add_f32_e32 v190, v190, v192
	v_mov_b32_e32 v191, v190
	s_nop 1
	v_permlane16_swap_b32_e32 v190, v191
	v_add_f32_e32 v190, v190, v191
	v_mov_b32_e32 v191, v190
	s_nop 1
	v_permlane32_swap_b32_e32 v190, v191
	v_add_f32_e32 v190, v190, v191
	v_fma_f32 v190, v190, s82, v252
	v_rsq_f32_e32 v190, v190
	s_nop 0
	v_cndmask_b32_e64 v178, 0, v190, s[52:53]
	s_waitcnt vmcnt(10)
	v_add_f32_e32 v194, v194, v195
	v_add_f32_e32 v196, v196, v197
	v_add_f32_e32 v194, v194, v196
	v_mov_b32_e32 v195, v194
	s_nop 1
	v_permlane16_swap_b32_e32 v194, v195
	v_add_f32_e32 v194, v194, v195
	v_mov_b32_e32 v195, v194
	s_nop 1
	v_permlane32_swap_b32_e32 v194, v195
	v_add_f32_e32 v194, v194, v195
	v_fma_f32 v194, v194, s82, v252
	v_rsq_f32_e32 v194, v194
	s_nop 0
	v_cndmask_b32_e64 v180, 0, v194, s[64:65]
	s_waitcnt vmcnt(9)
	v_add_f32_e32 v198, v198, v199
	v_add_f32_e32 v200, v200, v201
	v_add_f32_e32 v198, v198, v200
	v_mov_b32_e32 v199, v198
	s_nop 1
	v_permlane16_swap_b32_e32 v198, v199
	v_add_f32_e32 v198, v198, v199
	v_mov_b32_e32 v199, v198
	s_nop 1
	v_permlane32_swap_b32_e32 v198, v199
	v_add_f32_e32 v198, v198, v199
	v_fma_f32 v198, v198, s82, v252
	v_rsq_f32_e32 v198, v198
	s_nop 0
	v_cndmask_b32_e64 v182, 0, v198, s[98:99]
	s_waitcnt vmcnt(8)
; __device__ __forceinline__ float dpp_ror1(float x) { return __builtin_bit_cast(float, __builtin_amdgcn_mov_dpp(__builtin_bit_cast(int, x), 0x121, 0xF, 0xF, true)); }
;     __device__ __forceinline__ void operator()(const f32x4 (&acc)[2][2][4][2], const Unit& u, int wr, int wc, int fr, int fq) const {
;     ...
;             for (int m = 0; m < 4; ++m) { const int t = tbase + 16 * m + fr; const bool vin = (t >= 0) && (t < slen); const int grow = seqbase + (vin ? t : 0);
;                 const f32x4 p = *(const f32x4*)(PS + (size_t)grow * 16 + 4 * fq); float s = (p[0] + p[1]) + (p[2] + p[3]); s = bfly_add<16>(s); s = bfly_add<32>(s); rs[m] = vin ? rsqrtf(s * (1.f / DM) + EPS) : 0.f; }
;             unsigned outw[4][2][2];
; #pragma unroll
;             for (int n = 0; n < 2; ++n)
; #pragma unroll
;                 for (int jp = 0; jp < 2; ++jp) {
;                     const int cidx = (4 * n + 2 * jp) * 2;
;                     const f32x4 c0a = ct[cidx], c0b = ct[cidx + 1], c1a = ct[cidx + 2], c1b = ct[cidx + 3];
;                     const f32x2 wv0 = {c0a[0], c1a[0]}, wv1 = {c0a[1], c1a[1]}, wv2 = {c0a[2], c1a[2]}, bv = {c0a[3], c1a[3]};
;                     const f32x2 wg0 = {c0b[0], c1b[0]}, wg1 = {c0b[1], c1b[1]}, wg2 = {c0b[2], c1b[2]}, bg = {c0b[3], c1b[3]};
;                     f32x2 uv[4], ug[4], cv[4];
; #pragma unroll
;                     for (int m = 0; m < 4; ++m) { uv[m] = (f32x2){acc[ai][0][m][n][2 * jp], acc[ai][0][m][n][2 * jp + 1]}; ug[m] = (f32x2){acc[ai][1][m][n][2 * jp], acc[ai][1][m][n][2 * jp + 1]}; }
;                     asm volatile("" : "+v"(uv[0]), "+v"(uv[1]), "+v"(uv[2]), "+v"(uv[3]), "+v"(ug[0]), "+v"(ug[1]), "+v"(ug[2]), "+v"(ug[3]));
;                     {
;                         f32x2 rv[4], lv[4];
; #pragma unroll
;                         for (int m = 0; m < 4; ++m) { uv[m] = uv[m] * rs[m]; rv[m] = (f32x2){dpp_ror1(uv[m][0]), dpp_ror1(uv[m][1])}; lv[m] = (f32x2){dpp_ror15(uv[m][0]), dpp_ror15(uv[m][1])}; }
; #pragma unroll
;                         for (int m = 0; m < 4; ++m) { const f32x2 pv_ = (m > 0 && f0) ? rv[m > 0 ? m - 1 : 0] : rv[m], nv_ = (m < 3 && f15) ? lv[m < 3 ? m + 1 : 3] : lv[m];
;                             cv[m] = bv + wv0 * pv_ + wv1 * uv[m] + wv2 * nv_; }
	v_add_f32_e32 v202, v202, v203
	v_add_f32_e32 v204, v204, v205
	v_add_f32_e32 v202, v202, v204
	v_mov_b32_e32 v203, v202
	s_nop 1
	v_permlane16_swap_b32_e32 v202, v203
	v_add_f32_e32 v202, v202, v203
	v_mov_b32_e32 v203, v202
	s_nop 1
	v_permlane32_swap_b32_e32 v202, v203
	v_add_f32_e32 v202, v202, v203
	v_fma_f32 v202, v202, s82, v252
	v_rsq_f32_e32 v202, v202
	s_nop 0
	v_cndmask_b32_e64 v144, 0, v202, s[32:33]
	global_load_dwordx4 v[190:193], v172, s[100:101] offset:64
	global_load_dwordx4 v[194:197], v172, s[100:101] offset:80
	global_load_dwordx4 v[198:201], v172, s[100:101] offset:96
	global_load_dwordx4 v[202:205], v172, s[100:101] offset:112
	s_waitcnt vmcnt(4)
	v_pk_mul_f32 v[60:61], v[60:61], v[178:179] op_sel_hi:[1,0]
	v_pk_mul_f32 v[56:57], v[56:57], v[180:181] op_sel_hi:[1,0]
	v_pk_mul_f32 v[52:53], v[52:53], v[182:183] op_sel_hi:[1,0]
	v_pk_mul_f32 v[48:49], v[48:49], v[144:145] op_sel_hi:[1,0]
	v_pk_mul_f32 v[44:45], v[44:45], v[178:179] op_sel_hi:[1,0]
	v_pk_mul_f32 v[40:41], v[40:41], v[180:181] op_sel_hi:[1,0]
	v_pk_mul_f32 v[36:37], v[36:37], v[182:183] op_sel_hi:[1,0]
	v_pk_mul_f32 v[32:33], v[32:33], v[144:145] op_sel_hi:[1,0]
	s_nop 1
	v_mov_b32_dpp v248, v48 row_shr:1 row_mask:0xf bank_mask:0xf bound_ctrl:1
	v_mov_b32_dpp v249, v49 row_shr:1 row_mask:0xf bank_mask:0xf bound_ctrl:1
	v_mov_b32_dpp v250, v60 row_shl:1 row_mask:0xf bank_mask:0xf bound_ctrl:1
	v_mov_b32_dpp v251, v61 row_shl:1 row_mask:0xf bank_mask:0xf bound_ctrl:1
	v_pk_fma_f32 v[224:225], v[206:207], v[248:249], v[212:213]
	v_pk_fma_f32 v[226:227], v[206:207], v[60:61], v[212:213]
	v_pk_fma_f32 v[228:229], v[206:207], v[56:57], v[212:213]
	v_pk_fma_f32 v[230:231], v[206:207], v[52:53], v[212:213]
	v_pk_fma_f32 v[224:225], v[208:209], v[60:61], v[224:225]
	v_pk_fma_f32 v[226:227], v[208:209], v[56:57], v[226:227]
	v_pk_fma_f32 v[228:229], v[208:209], v[52:53], v[228:229]
	v_pk_fma_f32 v[230:231], v[208:209], v[48:49], v[230:231]
	v_pk_fma_f32 v[224:225], v[210:211], v[56:57], v[224:225]
	v_pk_fma_f32 v[226:227], v[210:211], v[52:53], v[226:227]
	v_pk_fma_f32 v[228:229], v[210:211], v[48:49], v[228:229]
	v_pk_fma_f32 v[230:231], v[210:211], v[250:251], v[230:231]
	s_nop 1
	v_mov_b32_dpp v248, v32 row_shr:1 row_mask:0xf bank_mask:0xf bound_ctrl:1
	v_mov_b32_dpp v249, v33 row_shr:1 row_mask:0xf bank_mask:0xf bound_ctrl:1
	v_mov_b32_dpp v250, v44 row_shl:1 row_mask:0xf bank_mask:0xf bound_ctrl:1
	v_mov_b32_dpp v251, v45 row_shl:1 row_mask:0xf bank_mask:0xf bound_ctrl:1
	v_pk_fma_f32 v[232:233], v[214:215], v[248:249], v[220:221]
	v_pk_fma_f32 v[234:235], v[214:215], v[44:45], v[220:221]
	v_pk_fma_f32 v[236:237], v[214:215], v[40:41], v[220:221]
	v_pk_fma_f32 v[238:239], v[214:215], v[36:37], v[220:221]
	v_pk_fma_f32 v[232:233], v[216:217], v[44:45], v[232:233]
	v_pk_fma_f32 v[234:235], v[216:217], v[40:41], v[234:235]
	v_pk_fma_f32 v[236:237], v[216:217], v[36:37], v[236:237]
	v_pk_fma_f32 v[238:239], v[216:217], v[32:33], v[238:239]
	v_pk_fma_f32 v[232:233], v[218:219], v[40:41], v[232:233]
	v_pk_fma_f32 v[234:235], v[218:219], v[36:37], v[234:235]
	v_pk_fma_f32 v[236:237], v[218:219], v[32:33], v[236:237]
	v_pk_fma_f32 v[238:239], v[218:219], v[250:251], v[238:239]
	v_exp_f32_e64 v240, -v232
	v_exp_f32_e64 v241, -v233
	v_exp_f32_e64 v242, -v234
	v_exp_f32_e64 v243, -v235
	v_exp_f32_e64 v244, -v236
	v_exp_f32_e64 v245, -v237
	v_exp_f32_e64 v246, -v238
	v_exp_f32_e64 v247, -v239
	v_pk_mul_f32 v[224:225], v[224:225], v[232:233]
	v_pk_mul_f32 v[226:227], v[226:227], v[234:235]
	v_pk_mul_f32 v[228:229], v[228:229], v[236:237]
	v_pk_mul_f32 v[230:231], v[230:231], v[238:239]
	v_pk_add_f32 v[240:241], v[240:241], 1.0 op_sel_hi:[1,0]
	v_pk_add_f32 v[242:243], v[242:243], 1.0 op_sel_hi:[1,0]
	v_pk_add_f32 v[244:245], v[244:245], 1.0 op_sel_hi:[1,0]
	v_pk_add_f32 v[246:247], v[246:247], 1.0 op_sel_hi:[1,0]
	v_rcp_f32_e32 v240, v240
	v_rcp_f32_e32 v241, v241
	v_rcp_f32_e32 v242, v242
	v_rcp_f32_e32 v243, v243
	v_rcp_f32_e32 v244, v244
	v_rcp_f32_e32 v245, v245
	v_rcp_f32_e32 v246, v246
	v_rcp_f32_e32 v247, v247
	s_nop 0
	v_pk_mul_f32 v[224:225], v[224:225], v[240:241]
	v_pk_mul_f32 v[226:227], v[226:227], v[242:243]
	v_pk_mul_f32 v[228:229], v[228:229], v[244:245]
	v_pk_mul_f32 v[230:231], v[230:231], v[246:247]
	v_cvt_pk_bf16_f32 v128, v224, v225
	v_cvt_pk_bf16_f32 v132, v226, v227
	v_cvt_pk_bf16_f32 v136, v228, v229
	v_cvt_pk_bf16_f32 v140, v230, v231
	global_load_dwordx4 v[206:209], v172, s[100:101] offset:128
	global_load_dwordx4 v[210:213], v172, s[100:101] offset:144
	global_load_dwordx4 v[214:217], v172, s[100:101] offset:160
	global_load_dwordx4 v[218:221], v172, s[100:101] offset:176
	s_waitcnt vmcnt(4)
; __device__ __forceinline__ unsigned cvtpk(float lo, float hi) { f32x2 v = {lo, hi}; bf16x2_t b = __builtin_convertvector(v, bf16x2_t); return __builtin_bit_cast(unsigned, b); }
; __device__ __forceinline__ float dpp_ror1(float x) { return __builtin_bit_cast(float, __builtin_amdgcn_mov_dpp(__builtin_bit_cast(int, x), 0x121, 0xF, 0xF, true)); }
; __device__ __forceinline__ float dpp_ror15(float x) { return __builtin_bit_cast(float, __builtin_amdgcn_mov_dpp(__builtin_bit_cast(int, x), 0x12F, 0xF, 0xF, true)); }
;     __device__ __forceinline__ void operator()(const f32x4 (&acc)[2][2][4][2], const Unit& u, int wr, int wc, int fr, int fq) const {
;     ...
;                         for (int m = 0; m < 4; ++m) { uv[m] = uv[m] * rs[m]; rv[m] = (f32x2){dpp_ror1(uv[m][0]), dpp_ror1(uv[m][1])}; lv[m] = (f32x2){dpp_ror15(uv[m][0]), dpp_ror15(uv[m][1])}; }
; #pragma unroll
;                         for (int m = 0; m < 4; ++m) { const f32x2 pv_ = (m > 0 && f0) ? rv[m > 0 ? m - 1 : 0] : rv[m], nv_ = (m < 3 && f15) ? lv[m < 3 ? m + 1 : 3] : lv[m];
;                             cv[m] = bv + wv0 * pv_ + wv1 * uv[m] + wv2 * nv_; }
;                     }
;                     asm volatile("" : "+v"(cv[0]), "+v"(cv[1]), "+v"(cv[2]), "+v"(cv[3]));
;                     {
;                         f32x2 rg[4], lg[4];
; #pragma unroll
;                         for (int m = 0; m < 4; ++m) { ug[m] = ug[m] * rs[m]; rg[m] = (f32x2){dpp_ror1(ug[m][0]), dpp_ror1(ug[m][1])}; lg[m] = (f32x2){dpp_ror15(ug[m][0]), dpp_ror15(ug[m][1])}; }
; #pragma unroll
;                         for (int m = 0; m < 4; ++m) { const f32x2 pg_ = (m > 0 && f0) ? rg[m > 0 ? m - 1 : 0] : rg[m], ng_ = (m < 3 && f15) ? lg[m < 3 ? m + 1 : 3] : lg[m];
;                             const f32x2 cgt = bg + wg0 * pg_ + wg1 * ug[m] + wg2 * ng_;
;                             const f32x2 e = cgt * (-LOG2E);
;                             const f32x2 d = (f32x2){__builtin_amdgcn_exp2f(e[0]), __builtin_amdgcn_exp2f(e[1])} + 1.f;
;                             const f32x2 sg = {__builtin_amdgcn_rcpf(d[0]), __builtin_amdgcn_rcpf(d[1])};
;                             const f32x2 ov = cv[m] * cgt * sg;
;                             outw[m][n][jp] = cvtpk(ov[0], ov[1]); }
	v_pk_mul_f32 v[62:63], v[62:63], v[178:179] op_sel_hi:[1,0]
	v_pk_mul_f32 v[58:59], v[58:59], v[180:181] op_sel_hi:[1,0]
	v_pk_mul_f32 v[54:55], v[54:55], v[182:183] op_sel_hi:[1,0]
	v_pk_mul_f32 v[50:51], v[50:51], v[144:145] op_sel_hi:[1,0]
	v_pk_mul_f32 v[46:47], v[46:47], v[178:179] op_sel_hi:[1,0]
	v_pk_mul_f32 v[42:43], v[42:43], v[180:181] op_sel_hi:[1,0]
	v_pk_mul_f32 v[38:39], v[38:39], v[182:183] op_sel_hi:[1,0]
	v_pk_mul_f32 v[34:35], v[34:35], v[144:145] op_sel_hi:[1,0]
	s_nop 1
	v_mov_b32_dpp v248, v50 row_shr:1 row_mask:0xf bank_mask:0xf bound_ctrl:1
	v_mov_b32_dpp v249, v51 row_shr:1 row_mask:0xf bank_mask:0xf bound_ctrl:1
	v_mov_b32_dpp v250, v62 row_shl:1 row_mask:0xf bank_mask:0xf bound_ctrl:1
	v_mov_b32_dpp v251, v63 row_shl:1 row_mask:0xf bank_mask:0xf bound_ctrl:1
	v_pk_fma_f32 v[224:225], v[190:191], v[248:249], v[196:197]
	v_pk_fma_f32 v[226:227], v[190:191], v[62:63], v[196:197]
	v_pk_fma_f32 v[228:229], v[190:191], v[58:59], v[196:197]
	v_pk_fma_f32 v[230:231], v[190:191], v[54:55], v[196:197]
	v_pk_fma_f32 v[224:225], v[192:193], v[62:63], v[224:225]
	v_pk_fma_f32 v[226:227], v[192:193], v[58:59], v[226:227]
	v_pk_fma_f32 v[228:229], v[192:193], v[54:55], v[228:229]
	v_pk_fma_f32 v[230:231], v[192:193], v[50:51], v[230:231]
	v_pk_fma_f32 v[224:225], v[194:195], v[58:59], v[224:225]
	v_pk_fma_f32 v[226:227], v[194:195], v[54:55], v[226:227]
	v_pk_fma_f32 v[228:229], v[194:195], v[50:51], v[228:229]
	v_pk_fma_f32 v[230:231], v[194:195], v[250:251], v[230:231]
	s_nop 1
	v_mov_b32_dpp v248, v34 row_shr:1 row_mask:0xf bank_mask:0xf bound_ctrl:1
	v_mov_b32_dpp v249, v35 row_shr:1 row_mask:0xf bank_mask:0xf bound_ctrl:1
	v_mov_b32_dpp v250, v46 row_shl:1 row_mask:0xf bank_mask:0xf bound_ctrl:1
	v_mov_b32_dpp v251, v47 row_shl:1 row_mask:0xf bank_mask:0xf bound_ctrl:1
	v_pk_fma_f32 v[232:233], v[198:199], v[248:249], v[204:205]
	v_pk_fma_f32 v[234:235], v[198:199], v[46:47], v[204:205]
	v_pk_fma_f32 v[236:237], v[198:199], v[42:43], v[204:205]
	v_pk_fma_f32 v[238:239], v[198:199], v[38:39], v[204:205]
	v_pk_fma_f32 v[232:233], v[200:201], v[46:47], v[232:233]
	v_pk_fma_f32 v[234:235], v[200:201], v[42:43], v[234:235]
	v_pk_fma_f32 v[236:237], v[200:201], v[38:39], v[236:237]
	v_pk_fma_f32 v[238:239], v[200:201], v[34:35], v[238:239]
	v_pk_fma_f32 v[232:233], v[202:203], v[42:43], v[232:233]
	v_pk_fma_f32 v[234:235], v[202:203], v[38:39], v[234:235]
	v_pk_fma_f32 v[236:237], v[202:203], v[34:35], v[236:237]
	v_pk_fma_f32 v[238:239], v[202:203], v[250:251], v[238:239]
	v_exp_f32_e64 v240, -v232
	v_exp_f32_e64 v241, -v233
	v_exp_f32_e64 v242, -v234
	v_exp_f32_e64 v243, -v235
	v_exp_f32_e64 v244, -v236
	v_exp_f32_e64 v245, -v237
	v_exp_f32_e64 v246, -v238
	v_exp_f32_e64 v247, -v239
	v_pk_mul_f32 v[224:225], v[224:225], v[232:233]
	v_pk_mul_f32 v[226:227], v[226:227], v[234:235]
	v_pk_mul_f32 v[228:229], v[228:229], v[236:237]
	v_pk_mul_f32 v[230:231], v[230:231], v[238:239]
	v_pk_add_f32 v[240:241], v[240:241], 1.0 op_sel_hi:[1,0]
	v_pk_add_f32 v[242:243], v[242:243], 1.0 op_sel_hi:[1,0]
	v_pk_add_f32 v[244:245], v[244:245], 1.0 op_sel_hi:[1,0]
	v_pk_add_f32 v[246:247], v[246:247], 1.0 op_sel_hi:[1,0]
	v_rcp_f32_e32 v240, v240
	v_rcp_f32_e32 v241, v241
	v_rcp_f32_e32 v242, v242
	v_rcp_f32_e32 v243, v243
	v_rcp_f32_e32 v244, v244
	v_rcp_f32_e32 v245, v245
	v_rcp_f32_e32 v246, v246
	v_rcp_f32_e32 v247, v247
	s_nop 0
	v_pk_mul_f32 v[224:225], v[224:225], v[240:241]
	v_pk_mul_f32 v[226:227], v[226:227], v[242:243]
	v_pk_mul_f32 v[228:229], v[228:229], v[244:245]
	v_pk_mul_f32 v[230:231], v[230:231], v[246:247]
	v_cvt_pk_bf16_f32 v129, v224, v225
	v_cvt_pk_bf16_f32 v133, v226, v227
	v_cvt_pk_bf16_f32 v137, v228, v229
	v_cvt_pk_bf16_f32 v141, v230, v231
	global_load_dwordx4 v[190:193], v172, s[100:101] offset:192
	global_load_dwordx4 v[194:197], v172, s[100:101] offset:208
	global_load_dwordx4 v[198:201], v172, s[100:101] offset:224
	global_load_dwordx4 v[202:205], v172, s[100:101] offset:240
	s_waitcnt vmcnt(4)
	v_pk_mul_f32 v[28:29], v[28:29], v[178:179] op_sel_hi:[1,0]
	v_pk_mul_f32 v[24:25], v[24:25], v[180:181] op_sel_hi:[1,0]
	v_pk_mul_f32 v[20:21], v[20:21], v[182:183] op_sel_hi:[1,0]
	v_pk_mul_f32 v[16:17], v[16:17], v[144:145] op_sel_hi:[1,0]
	v_pk_mul_f32 v[12:13], v[12:13], v[178:179] op_sel_hi:[1,0]
	v_pk_mul_f32 v[8:9], v[8:9], v[180:181] op_sel_hi:[1,0]
	v_pk_mul_f32 v[4:5], v[4:5], v[182:183] op_sel_hi:[1,0]
	v_pk_mul_f32 v[0:1], v[0:1], v[144:145] op_sel_hi:[1,0]
	s_nop 1
	v_mov_b32_dpp v248, v16 row_shr:1 row_mask:0xf bank_mask:0xf bound_ctrl:1
	v_mov_b32_dpp v249, v17 row_shr:1 row_mask:0xf bank_mask:0xf bound_ctrl:1
	v_mov_b32_dpp v250, v28 row_shl:1 row_mask:0xf bank_mask:0xf bound_ctrl:1
	v_mov_b32_dpp v251, v29 row_shl:1 row_mask:0xf bank_mask:0xf bound_ctrl:1
	v_pk_fma_f32 v[224:225], v[206:207], v[248:249], v[212:213]
	v_pk_fma_f32 v[226:227], v[206:207], v[28:29], v[212:213]
	v_pk_fma_f32 v[228:229], v[206:207], v[24:25], v[212:213]
	v_pk_fma_f32 v[230:231], v[206:207], v[20:21], v[212:213]
	v_pk_fma_f32 v[224:225], v[208:209], v[28:29], v[224:225]
	v_pk_fma_f32 v[226:227], v[208:209], v[24:25], v[226:227]
	v_pk_fma_f32 v[228:229], v[208:209], v[20:21], v[228:229]
	v_pk_fma_f32 v[230:231], v[208:209], v[16:17], v[230:231]
	v_pk_fma_f32 v[224:225], v[210:211], v[24:25], v[224:225]
	v_pk_fma_f32 v[226:227], v[210:211], v[20:21], v[226:227]
	v_pk_fma_f32 v[228:229], v[210:211], v[16:17], v[228:229]
	v_pk_fma_f32 v[230:231], v[210:211], v[250:251], v[230:231]
	s_nop 1
	v_mov_b32_dpp v248, v0 row_shr:1 row_mask:0xf bank_mask:0xf bound_ctrl:1
	v_mov_b32_dpp v249, v1 row_shr:1 row_mask:0xf bank_mask:0xf bound_ctrl:1
;     __device__ __forceinline__ void operator()(const f32x4 (&acc)[2][2][4][2], const Unit& u, int wr, int wc, int fr, int fq) const {
;     ...
;                         for (int m = 0; m < 4; ++m) { uv[m] = uv[m] * rs[m]; rv[m] = (f32x2){dpp_ror1(uv[m][0]), dpp_ror1(uv[m][1])}; lv[m] = (f32x2){dpp_ror15(uv[m][0]), dpp_ror15(uv[m][1])}; }
; #pragma unroll
;                         for (int m = 0; m < 4; ++m) { const f32x2 pv_ = (m > 0 && f0) ? rv[m > 0 ? m - 1 : 0] : rv[m], nv_ = (m < 3 && f15) ? lv[m < 3 ? m + 1 : 3] : lv[m];
;                             cv[m] = bv + wv0 * pv_ + wv1 * uv[m] + wv2 * nv_; }
;                     }
;                     asm volatile("" : "+v"(cv[0]), "+v"(cv[1]), "+v"(cv[2]), "+v"(cv[3]));
;                     {
;                         f32x2 rg[4], lg[4];
; #pragma unroll
;                         for (int m = 0; m < 4; ++m) { ug[m] = ug[m] * rs[m]; rg[m] = (f32x2){dpp_ror1(ug[m][0]), dpp_ror1(ug[m][1])}; lg[m] = (f32x2){dpp_ror15(ug[m][0]), dpp_ror15(ug[m][1])}; }
; #pragma unroll
;                         for (int m = 0; m < 4; ++m) { const f32x2 pg_ = (m > 0 && f0) ? rg[m > 0 ? m - 1 : 0] : rg[m], ng_ = (m < 3 && f15) ? lg[m < 3 ? m + 1 : 3] : lg[m];
;                             const f32x2 cgt = bg + wg0 * pg_ + wg1 * ug[m] + wg2 * ng_;
;                             const f32x2 e = cgt * (-LOG2E);
;                             const f32x2 d = (f32x2){__builtin_amdgcn_exp2f(e[0]), __builtin_amdgcn_exp2f(e[1])} + 1.f;
;                             const f32x2 sg = {__builtin_amdgcn_rcpf(d[0]), __builtin_amdgcn_rcpf(d[1])};
;                             const f32x2 ov = cv[m] * cgt * sg;
;                             outw[m][n][jp] = cvtpk(ov[0], ov[1]); }
;                     }
;                     asm volatile("" : "+v"(outw[0][n][jp]), "+v"(outw[1][n][jp]), "+v"(outw[2][n][jp]), "+v"(outw[3][n][jp]) :: "memory"); __builtin_amdgcn_sched_barrier(0);
;                 }
; #pragma unroll
;             for (int m = 0; m < 4; ++m) { const int i = 16 * m + fr, t = tbase + i;
;                 if (i >= 1 && i <= 62 && t < slen) { u32x4 w; w.x = outw[m][0][0]; w.y = outw[m][0][1]; w.z = outw[m][1][0]; w.w = outw[m][1][1];
;                     *(u32x4*)(Gout + (size_t)(seqbase + t) * DFF + 128 * u.pn + 32 * wc + 8 * fq) = w; } }
	v_mov_b32_dpp v250, v12 row_shl:1 row_mask:0xf bank_mask:0xf bound_ctrl:1
	v_mov_b32_dpp v251, v13 row_shl:1 row_mask:0xf bank_mask:0xf bound_ctrl:1
	v_pk_fma_f32 v[232:233], v[214:215], v[248:249], v[220:221]
	v_pk_fma_f32 v[234:235], v[214:215], v[12:13], v[220:221]
	v_pk_fma_f32 v[236:237], v[214:215], v[8:9], v[220:221]
	v_pk_fma_f32 v[238:239], v[214:215], v[4:5], v[220:221]
	v_pk_fma_f32 v[232:233], v[216:217], v[12:13], v[232:233]
	v_pk_fma_f32 v[234:235], v[216:217], v[8:9], v[234:235]
	v_pk_fma_f32 v[236:237], v[216:217], v[4:5], v[236:237]
	v_pk_fma_f32 v[238:239], v[216:217], v[0:1], v[238:239]
	v_pk_fma_f32 v[232:233], v[218:219], v[8:9], v[232:233]
	v_pk_fma_f32 v[234:235], v[218:219], v[4:5], v[234:235]
	v_pk_fma_f32 v[236:237], v[218:219], v[0:1], v[236:237]
	v_pk_fma_f32 v[238:239], v[218:219], v[250:251], v[238:239]
	v_exp_f32_e64 v240, -v232
	v_exp_f32_e64 v241, -v233
	v_exp_f32_e64 v242, -v234
	v_exp_f32_e64 v243, -v235
	v_exp_f32_e64 v244, -v236
	v_exp_f32_e64 v245, -v237
	v_exp_f32_e64 v246, -v238
	v_exp_f32_e64 v247, -v239
	v_pk_mul_f32 v[224:225], v[224:225], v[232:233]
	v_pk_mul_f32 v[226:227], v[226:227], v[234:235]
	v_pk_mul_f32 v[228:229], v[228:229], v[236:237]
	v_pk_mul_f32 v[230:231], v[230:231], v[238:239]
	v_pk_add_f32 v[240:241], v[240:241], 1.0 op_sel_hi:[1,0]
	v_pk_add_f32 v[242:243], v[242:243], 1.0 op_sel_hi:[1,0]
	v_pk_add_f32 v[244:245], v[244:245], 1.0 op_sel_hi:[1,0]
	v_pk_add_f32 v[246:247], v[246:247], 1.0 op_sel_hi:[1,0]
	v_rcp_f32_e32 v240, v240
	v_rcp_f32_e32 v241, v241
	v_rcp_f32_e32 v242, v242
	v_rcp_f32_e32 v243, v243
	v_rcp_f32_e32 v244, v244
	v_rcp_f32_e32 v245, v245
	v_rcp_f32_e32 v246, v246
	v_rcp_f32_e32 v247, v247
	s_nop 0
	v_pk_mul_f32 v[224:225], v[224:225], v[240:241]
	v_pk_mul_f32 v[226:227], v[226:227], v[242:243]
	v_pk_mul_f32 v[228:229], v[228:229], v[244:245]
	v_pk_mul_f32 v[230:231], v[230:231], v[246:247]
	v_cvt_pk_bf16_f32 v130, v224, v225
	v_cvt_pk_bf16_f32 v134, v226, v227
	v_cvt_pk_bf16_f32 v138, v228, v229
	v_cvt_pk_bf16_f32 v142, v230, v231
	s_waitcnt vmcnt(0)
	v_pk_mul_f32 v[30:31], v[30:31], v[178:179] op_sel_hi:[1,0]
	v_pk_mul_f32 v[26:27], v[26:27], v[180:181] op_sel_hi:[1,0]
	v_pk_mul_f32 v[22:23], v[22:23], v[182:183] op_sel_hi:[1,0]
	v_pk_mul_f32 v[18:19], v[18:19], v[144:145] op_sel_hi:[1,0]
	v_pk_mul_f32 v[14:15], v[14:15], v[178:179] op_sel_hi:[1,0]
	v_pk_mul_f32 v[10:11], v[10:11], v[180:181] op_sel_hi:[1,0]
	v_pk_mul_f32 v[6:7], v[6:7], v[182:183] op_sel_hi:[1,0]
	v_pk_mul_f32 v[2:3], v[2:3], v[144:145] op_sel_hi:[1,0]
	s_nop 1
	v_mov_b32_dpp v248, v18 row_shr:1 row_mask:0xf bank_mask:0xf bound_ctrl:1
	v_mov_b32_dpp v249, v19 row_shr:1 row_mask:0xf bank_mask:0xf bound_ctrl:1
	v_mov_b32_dpp v250, v30 row_shl:1 row_mask:0xf bank_mask:0xf bound_ctrl:1
	v_mov_b32_dpp v251, v31 row_shl:1 row_mask:0xf bank_mask:0xf bound_ctrl:1
	v_pk_fma_f32 v[224:225], v[190:191], v[248:249], v[196:197]
	v_pk_fma_f32 v[226:227], v[190:191], v[30:31], v[196:197]
	v_pk_fma_f32 v[228:229], v[190:191], v[26:27], v[196:197]
	v_pk_fma_f32 v[230:231], v[190:191], v[22:23], v[196:197]
	v_pk_fma_f32 v[224:225], v[192:193], v[30:31], v[224:225]
	v_pk_fma_f32 v[226:227], v[192:193], v[26:27], v[226:227]
	v_pk_fma_f32 v[228:229], v[192:193], v[22:23], v[228:229]
	v_pk_fma_f32 v[230:231], v[192:193], v[18:19], v[230:231]
	v_pk_fma_f32 v[224:225], v[194:195], v[26:27], v[224:225]
	v_pk_fma_f32 v[226:227], v[194:195], v[22:23], v[226:227]
	v_pk_fma_f32 v[228:229], v[194:195], v[18:19], v[228:229]
	v_pk_fma_f32 v[230:231], v[194:195], v[250:251], v[230:231]
	s_nop 1
	v_mov_b32_dpp v248, v2 row_shr:1 row_mask:0xf bank_mask:0xf bound_ctrl:1
	v_mov_b32_dpp v249, v3 row_shr:1 row_mask:0xf bank_mask:0xf bound_ctrl:1
	v_mov_b32_dpp v250, v14 row_shl:1 row_mask:0xf bank_mask:0xf bound_ctrl:1
	v_mov_b32_dpp v251, v15 row_shl:1 row_mask:0xf bank_mask:0xf bound_ctrl:1
	v_pk_fma_f32 v[232:233], v[198:199], v[248:249], v[204:205]
	v_pk_fma_f32 v[234:235], v[198:199], v[14:15], v[204:205]
	v_pk_fma_f32 v[236:237], v[198:199], v[10:11], v[204:205]
	v_pk_fma_f32 v[238:239], v[198:199], v[6:7], v[204:205]
	v_pk_fma_f32 v[232:233], v[200:201], v[14:15], v[232:233]
	v_pk_fma_f32 v[234:235], v[200:201], v[10:11], v[234:235]
	v_pk_fma_f32 v[236:237], v[200:201], v[6:7], v[236:237]
	v_pk_fma_f32 v[238:239], v[200:201], v[2:3], v[238:239]
	v_pk_fma_f32 v[232:233], v[202:203], v[10:11], v[232:233]
	v_pk_fma_f32 v[234:235], v[202:203], v[6:7], v[234:235]
	v_pk_fma_f32 v[236:237], v[202:203], v[2:3], v[236:237]
	v_pk_fma_f32 v[238:239], v[202:203], v[250:251], v[238:239]
	v_exp_f32_e64 v240, -v232
	v_exp_f32_e64 v241, -v233
	v_exp_f32_e64 v242, -v234
	v_exp_f32_e64 v243, -v235
	v_exp_f32_e64 v244, -v236
	v_exp_f32_e64 v245, -v237
	v_exp_f32_e64 v246, -v238
	v_exp_f32_e64 v247, -v239
	v_pk_mul_f32 v[224:225], v[224:225], v[232:233]
	v_pk_mul_f32 v[226:227], v[226:227], v[234:235]
	v_pk_mul_f32 v[228:229], v[228:229], v[236:237]
	v_pk_mul_f32 v[230:231], v[230:231], v[238:239]
	v_pk_add_f32 v[240:241], v[240:241], 1.0 op_sel_hi:[1,0]
	v_pk_add_f32 v[242:243], v[242:243], 1.0 op_sel_hi:[1,0]
	v_pk_add_f32 v[244:245], v[244:245], 1.0 op_sel_hi:[1,0]
	v_pk_add_f32 v[246:247], v[246:247], 1.0 op_sel_hi:[1,0]
	v_rcp_f32_e32 v240, v240
	v_rcp_f32_e32 v241, v241
	v_rcp_f32_e32 v242, v242
	v_rcp_f32_e32 v243, v243
	v_rcp_f32_e32 v244, v244
	v_rcp_f32_e32 v245, v245
	v_rcp_f32_e32 v246, v246
	v_rcp_f32_e32 v247, v247
	s_nop 0
	v_pk_mul_f32 v[224:225], v[224:225], v[240:241]
	v_pk_mul_f32 v[226:227], v[226:227], v[242:243]
	v_pk_mul_f32 v[228:229], v[228:229], v[244:245]
	v_pk_mul_f32 v[230:231], v[230:231], v[246:247]
	v_cvt_pk_bf16_f32 v131, v224, v225
	v_cvt_pk_bf16_f32 v135, v226, v227
	v_cvt_pk_bf16_f32 v139, v228, v229
	v_cvt_pk_bf16_f32 v143, v230, v231
	s_sub_i32 s51, s91, s89
	s_sub_i32 s66, s51, 4
	s_max_i32 s66, s66, 0
	v_add_u32_e32 v176, -4, v170
	v_cmp_gt_u32_e32 vcc, s66, v176
	v_add_u32_e32 v176, 0, v174
	v_add_u32_e32 v176, s88, v176
	v_mad_u32_u24 v248, v176, s54, v171
	s_mov_b64 exec, vcc
	global_store_dwordx4 v248, v[128:131], s[86:87]
	s_mov_b64 exec, -1
	s_sub_i32 s66, s51, 1
	s_max_i32 s66, s66, 0
	v_cmp_gt_u32_e32 vcc, s66, v170
	v_add_u32_e32 v176, 1, v174
	v_add_u32_e32 v176, s88, v176
	v_mad_u32_u24 v249, v176, s54, v171
	s_mov_b64 exec, vcc
	global_store_dwordx4 v249, v[132:135], s[86:87]
	s_mov_b64 exec, -1
	s_sub_i32 s66, s51, 2
	s_max_i32 s66, s66, 0
	v_cmp_gt_u32_e32 vcc, s66, v170
	v_add_u32_e32 v176, 2, v174
	v_add_u32_e32 v176, s88, v176
	v_mad_u32_u24 v250, v176, s54, v171
	s_mov_b64 exec, vcc
	global_store_dwordx4 v250, v[136:139], s[86:87]
	s_mov_b64 exec, -1
	s_sub_i32 s66, s51, 3
	s_min_i32 s66, s66, 60
	s_max_i32 s66, s66, 0
	v_cmp_gt_u32_e32 vcc, s66, v170
	v_add_u32_e32 v176, 3, v174
	v_add_u32_e32 v176, s88, v176
	v_mad_u32_u24 v251, v176, s54, v171
	s_mov_b64 exec, vcc
	global_store_dwordx4 v251, v[140:143], s[86:87]
	s_mov_b64 exec, -1
	s_mov_b64 s[2:3], exec
